# row-scale dwordx4 ladders in phase-1 V epilogue and kv-tile variant: next group's load issued one group ahead into spare quad, counted waits (no store drain), on top of v_ssq
# baseline (speedup 1.0000x reference)
.LBB0_208:
	s_add_i32 s27, s5, 64
	s_min_u32 s30, s27, 0x3e0
	s_lshl_b32 s30, s30, 1
	v_lshl_add_u64 v[180:181], v[154:155], 0, s[30:31]
	v_lshl_add_u64 v[184:185], v[158:159], 0, s[30:31]
	v_lshl_add_u64 v[188:189], v[160:161], 0, s[30:31]
	v_lshl_add_u64 v[192:193], v[162:163], 0, s[30:31]
	v_lshl_add_u64 v[196:197], v[156:157], 0, s[30:31]
	v_lshl_add_u64 v[200:201], v[164:165], 0, s[30:31]
	global_load_dwordx4 v[180:183], v[180:181], off
	ds_read_b128 v[204:207], v178 offset:32768
	global_load_dwordx4 v[184:187], v[184:185], off
	ds_read_b128 v[208:211], v178 offset:33792
	global_load_dwordx4 v[188:191], v[188:189], off
	ds_read_b128 v[212:215], v178 offset:34816
	global_load_dwordx4 v[192:195], v[192:193], off
	ds_read_b128 v[216:219], v178 offset:35840
	global_load_dwordx4 v[196:199], v[196:197], off
	ds_read_b128 v[222:225], v176
	global_load_dwordx4 v[200:203], v[200:201], off
	ds_read_b128 v[226:229], v176 offset:1024
	ds_read_b128 v[230:233], v176 offset:2048
	ds_read_b128 v[234:237], v176 offset:3072
	ds_read_b128 v[238:241], v176 offset:4096
	ds_read_b128 v[242:245], v176 offset:5120
	ds_read_b128 v[246:249], v176 offset:6144
	ds_read_b128 v[250:253], v176 offset:7168
	s_setprio 1
	s_waitcnt lgkmcnt(7)
	v_mfma_f32_16x16x32_bf16 v[124:127], v[222:225], v[204:207], v[124:127]
	v_mfma_f32_16x16x32_bf16 v[120:123], v[222:225], v[208:211], v[120:123]
	v_mfma_f32_16x16x32_bf16 v[60:63], v[222:225], v[212:215], v[60:63]
	v_mfma_f32_16x16x32_bf16 v[56:59], v[222:225], v[216:219], v[56:59]
	s_waitcnt vmcnt(11)
	ds_write_b128 v152, v[128:131] offset:16384
	s_waitcnt lgkmcnt(7)
	v_mfma_f32_16x16x32_bf16 v[116:119], v[226:229], v[204:207], v[116:119]
	v_mfma_f32_16x16x32_bf16 v[112:115], v[226:229], v[208:211], v[112:115]
	v_mfma_f32_16x16x32_bf16 v[52:55], v[226:229], v[212:215], v[52:55]
	v_mfma_f32_16x16x32_bf16 v[48:51], v[226:229], v[216:219], v[48:51]
	s_waitcnt vmcnt(9)
	ds_write_b128 v152, v[136:139] offset:20480
	s_waitcnt lgkmcnt(7)
	v_mfma_f32_16x16x32_bf16 v[108:111], v[230:233], v[204:207], v[108:111]
	v_mfma_f32_16x16x32_bf16 v[104:107], v[230:233], v[208:211], v[104:107]
	v_mfma_f32_16x16x32_bf16 v[44:47], v[230:233], v[212:215], v[44:47]
	v_mfma_f32_16x16x32_bf16 v[40:43], v[230:233], v[216:219], v[40:43]
	s_waitcnt vmcnt(8)
	ds_write_b128 v152, v[140:143] offset:24576
	s_waitcnt lgkmcnt(7)
	v_mfma_f32_16x16x32_bf16 v[100:103], v[234:237], v[204:207], v[100:103]
	v_mfma_f32_16x16x32_bf16 v[96:99], v[234:237], v[208:211], v[96:99]
	v_mfma_f32_16x16x32_bf16 v[36:39], v[234:237], v[212:215], v[36:39]
	v_mfma_f32_16x16x32_bf16 v[32:35], v[234:237], v[216:219], v[32:35]
	s_waitcnt vmcnt(7)
	ds_write_b128 v152, v[144:147] offset:28672
	s_waitcnt lgkmcnt(7)
	v_mfma_f32_16x16x32_bf16 v[92:95], v[238:241], v[204:207], v[92:95]
	v_mfma_f32_16x16x32_bf16 v[88:91], v[238:241], v[208:211], v[88:91]
	v_mfma_f32_16x16x32_bf16 v[28:31], v[238:241], v[212:215], v[28:31]
	v_mfma_f32_16x16x32_bf16 v[24:27], v[238:241], v[216:219], v[24:27]
	s_waitcnt vmcnt(7)
	ds_write_b128 v152, v[132:135] offset:40960
	s_waitcnt lgkmcnt(7)
	v_mfma_f32_16x16x32_bf16 v[84:87], v[242:245], v[204:207], v[84:87]
	v_mfma_f32_16x16x32_bf16 v[80:83], v[242:245], v[208:211], v[80:83]
	v_mfma_f32_16x16x32_bf16 v[20:23], v[242:245], v[212:215], v[20:23]
	v_mfma_f32_16x16x32_bf16 v[16:19], v[242:245], v[216:219], v[16:19]
	s_waitcnt vmcnt(6)
	ds_write_b128 v152, v[148:151] offset:45056
	s_waitcnt lgkmcnt(7)
	v_mfma_f32_16x16x32_bf16 v[76:79], v[246:249], v[204:207], v[76:79]
	v_mfma_f32_16x16x32_bf16 v[72:75], v[246:249], v[208:211], v[72:75]
	v_mfma_f32_16x16x32_bf16 v[12:15], v[246:249], v[212:215], v[12:15]
	v_mfma_f32_16x16x32_bf16 v[8:11], v[246:249], v[216:219], v[8:11]
	s_waitcnt lgkmcnt(6)
	v_mfma_f32_16x16x32_bf16 v[68:71], v[250:253], v[204:207], v[68:71]
	v_mfma_f32_16x16x32_bf16 v[64:67], v[250:253], v[208:211], v[64:67]
	v_mfma_f32_16x16x32_bf16 v[4:7], v[250:253], v[212:215], v[4:7]
	v_mfma_f32_16x16x32_bf16 v[0:3], v[250:253], v[216:219], v[0:3]
	s_setprio 0
	s_min_u32 s5, s5, 0x380
	s_lshl_b32 s30, s5, 1
	s_mov_b32 s53, s31
	s_add_i32 s52, s30, 0xc0
	v_lshl_add_u64 v[128:129], v[154:155], 0, s[30:31]
	v_lshl_add_u64 v[132:133], v[156:157], 0, s[30:31]
	v_lshl_add_u64 v[136:137], v[158:159], 0, s[52:53]
	v_lshl_add_u64 v[140:141], v[160:161], 0, s[52:53]
	v_lshl_add_u64 v[144:145], v[162:163], 0, s[52:53]
	v_lshl_add_u64 v[148:149], v[164:165], 0, s[52:53]
	s_waitcnt lgkmcnt(0)
	s_barrier
	global_load_dwordx4 v[128:131], v[128:129], off offset:192
	ds_read_b128 v[204:207], v175 offset:40960
	global_load_dwordx4 v[132:135], v[132:133], off offset:192
	ds_read_b128 v[208:211], v175 offset:41984
	global_load_dwordx4 v[136:139], v[136:137], off
	ds_read_b128 v[212:215], v175 offset:43008
	global_load_dwordx4 v[140:143], v[140:141], off
	ds_read_b128 v[216:219], v175 offset:44032
	global_load_dwordx4 v[144:147], v[144:145], off
	ds_read_b128 v[222:225], v177
	global_load_dwordx4 v[148:151], v[148:149], off
	ds_read_b128 v[226:229], v177 offset:1024
	ds_read_b128 v[230:233], v177 offset:2048
	ds_read_b128 v[234:237], v177 offset:3072
	ds_read_b128 v[238:241], v177 offset:4096
	ds_read_b128 v[242:245], v177 offset:5120
	ds_read_b128 v[246:249], v177 offset:6144
	ds_read_b128 v[250:253], v177 offset:7168
	s_setprio 1
	s_waitcnt lgkmcnt(7)
	v_mfma_f32_16x16x32_bf16 v[124:127], v[222:225], v[204:207], v[124:127]
	v_mfma_f32_16x16x32_bf16 v[120:123], v[222:225], v[208:211], v[120:123]
	v_mfma_f32_16x16x32_bf16 v[60:63], v[222:225], v[212:215], v[60:63]
	v_mfma_f32_16x16x32_bf16 v[56:59], v[222:225], v[216:219], v[56:59]
	s_waitcnt vmcnt(11)
	ds_write_b128 v152, v[180:183]
	s_waitcnt lgkmcnt(7)
	v_mfma_f32_16x16x32_bf16 v[116:119], v[226:229], v[204:207], v[116:119]
	v_mfma_f32_16x16x32_bf16 v[112:115], v[226:229], v[208:211], v[112:115]
	v_mfma_f32_16x16x32_bf16 v[52:55], v[226:229], v[212:215], v[52:55]
	v_mfma_f32_16x16x32_bf16 v[48:51], v[226:229], v[216:219], v[48:51]
	s_waitcnt vmcnt(10)
	ds_write_b128 v152, v[184:187] offset:4096
	s_waitcnt lgkmcnt(7)
	v_mfma_f32_16x16x32_bf16 v[108:111], v[230:233], v[204:207], v[108:111]
	v_mfma_f32_16x16x32_bf16 v[104:107], v[230:233], v[208:211], v[104:107]
	v_mfma_f32_16x16x32_bf16 v[44:47], v[230:233], v[212:215], v[44:47]
	v_mfma_f32_16x16x32_bf16 v[40:43], v[230:233], v[216:219], v[40:43]
	s_waitcnt vmcnt(9)
	ds_write_b128 v152, v[188:191] offset:8192
	s_waitcnt lgkmcnt(7)
	v_mfma_f32_16x16x32_bf16 v[100:103], v[234:237], v[204:207], v[100:103]
	v_mfma_f32_16x16x32_bf16 v[96:99], v[234:237], v[208:211], v[96:99]
	v_mfma_f32_16x16x32_bf16 v[36:39], v[234:237], v[212:215], v[36:39]
	v_mfma_f32_16x16x32_bf16 v[32:35], v[234:237], v[216:219], v[32:35]
	s_waitcnt vmcnt(8)
	ds_write_b128 v152, v[192:195] offset:12288
	s_waitcnt lgkmcnt(7)
	v_mfma_f32_16x16x32_bf16 v[92:95], v[238:241], v[204:207], v[92:95]
	v_mfma_f32_16x16x32_bf16 v[88:91], v[238:241], v[208:211], v[88:91]
	v_mfma_f32_16x16x32_bf16 v[28:31], v[238:241], v[212:215], v[28:31]
	v_mfma_f32_16x16x32_bf16 v[24:27], v[238:241], v[216:219], v[24:27]
	s_waitcnt vmcnt(7)
	ds_write_b128 v152, v[196:199] offset:32768
	s_waitcnt lgkmcnt(7)
	v_mfma_f32_16x16x32_bf16 v[84:87], v[242:245], v[204:207], v[84:87]
	v_mfma_f32_16x16x32_bf16 v[80:83], v[242:245], v[208:211], v[80:83]
	v_mfma_f32_16x16x32_bf16 v[20:23], v[242:245], v[212:215], v[20:23]
	v_mfma_f32_16x16x32_bf16 v[16:19], v[242:245], v[216:219], v[16:19]
	s_waitcnt vmcnt(6)
	ds_write_b128 v152, v[200:203] offset:36864
	s_waitcnt lgkmcnt(7)
	v_mfma_f32_16x16x32_bf16 v[76:79], v[246:249], v[204:207], v[76:79]
	v_mfma_f32_16x16x32_bf16 v[72:75], v[246:249], v[208:211], v[72:75]
	v_mfma_f32_16x16x32_bf16 v[12:15], v[246:249], v[212:215], v[12:15]
	v_mfma_f32_16x16x32_bf16 v[8:11], v[246:249], v[216:219], v[8:11]
	s_waitcnt lgkmcnt(6)
	v_mfma_f32_16x16x32_bf16 v[68:71], v[250:253], v[204:207], v[68:71]
	v_mfma_f32_16x16x32_bf16 v[64:67], v[250:253], v[208:211], v[64:67]
	v_mfma_f32_16x16x32_bf16 v[4:7], v[250:253], v[212:215], v[4:7]
	v_mfma_f32_16x16x32_bf16 v[0:3], v[250:253], v[216:219], v[0:3]
	s_setprio 0
	s_add_i32 s1, s1, 2
	s_cmp_lt_u32 s1, 30
	s_mov_b32 s5, s27
	s_waitcnt lgkmcnt(0)
	s_barrier
	s_cbranch_scc1 .LBB0_208
	s_waitcnt vmcnt(5)
	v_mov_b32_e32 v128, v220
	s_cmp_gt_i32 s26, 15
	v_and_b32_e32 v158, 15, v128
	v_and_b32_e32 v160, 64, v128
	v_and_b32_e32 v129, 0xffffff80, v128
	v_lshrrev_b32_e32 v128, 2, v128
	v_add_u32_e32 v130, s4, v129
	v_and_b32_e32 v159, 12, v128
	s_waitcnt vmcnt(3)
	v_or_b32_e32 v136, v130, v159
	v_ashrrev_i32_e32 v128, 14, v130
	s_waitcnt vmcnt(0)
	v_or_b32_e32 v150, 16, v136
	v_or_b32_e32 v148, 32, v136
	v_or_b32_e32 v146, 48, v136
	v_or_b32_e32 v142, 64, v136
	v_or_b32_e32 v140, 0x50, v136
	v_or_b32_e32 v138, 0x60, v136
	v_or_b32_e32 v134, 0x70, v136
	s_mov_b64 s[4:5], -1
	v_ashrrev_i32_e32 v137, 31, v136
	v_lshlrev_b32_e32 v132, 1, v159
	v_mov_b32_e32 v250, s0
	v_and_b32_e32 v250, 0x80, v250
	v_add_u32_e32 v250, v250, v160
	v_mul_u32_u24_e32 v250, 30, v250
	v_lshrrev_b32_e32 v251, 3, v158
	v_mul_u32_u24_e32 v251, 0xf0, v251
	v_add_u32_e32 v250, v250, v251
	v_lshrrev_b32_e32 v251, 2, v159
	v_mul_u32_u24_e32 v251, 0x7c0, v251
	v_sub_u32_e32 v250, v250, v251
	v_ashrrev_i32_e32 v251, 31, v250
	v_and_b32_e32 v252, 8, v159
	v_lshlrev_b32_e32 v252, 5, v252
	v_and_b32_e32 v253, 4, v159
	v_lshl_or_b32 v252, v253, 1, v252
	v_lshl_or_b32 v252, v158, 4, v252
	v_mov_b32_e32 v253, 0
	v_ashrrev_i32_e32 v129, 31, v128
	v_ashrrev_i32_e32 v151, 31, v150
	v_ashrrev_i32_e32 v149, 31, v148
	v_ashrrev_i32_e32 v147, 31, v146
	v_ashrrev_i32_e32 v143, 31, v142
	v_ashrrev_i32_e32 v141, 31, v140
	v_ashrrev_i32_e32 v139, 31, v138
	v_ashrrev_i32_e32 v135, 31, v134
	s_cbranch_scc0 .LBB0_211
	v_lshl_add_u64 v[144:145], v[136:137], 2, s[8:9]
	global_load_dwordx4 v[162:165], v[144:145], off
	s_add_i32 s1, s0, 0xfffff800
	s_and_b32 s5, s0, 0x180
	s_ashr_i32 s4, s1, 9
	v_or_b32_e32 v154, s5, v160
	s_ashr_i32 s5, s4, 31
	v_lshlrev_b64 v[144:145], 9, v[128:129]
	s_lshl_b64 s[4:5], s[4:5], 7
	v_lshrrev_b32_e32 v152, 7, v130
	v_lshl_add_u64 v[130:131], v[144:145], 0, s[4:5]
	v_and_or_b32 v130, v152, s38, v130
	v_lshlrev_b64 v[130:131], 16, v[130:131]
	v_mov_b32_e32 v133, v153
	v_lshl_or_b32 v130, v154, 7, v130
	v_lshl_add_u64 v[178:179], s[12:13], 0, v[252:253]
	v_mov_b32_e32 v145, v131
	v_mov_b32_e32 v181, v131
	v_lshlrev_b64 v[156:157], 1, v[130:131]
	v_or_b32_e32 v144, 0x800, v130
	v_or_b32_e32 v180, 0x1000, v130
	v_or_b32_e32 v130, 0x1800, v130
	v_lshl_add_u64 v[182:183], v[178:179], 0, v[156:157]
	v_lshlrev_b64 v[154:155], 1, v[144:145]
	v_lshlrev_b64 v[144:145], 1, v[180:181]
	v_lshlrev_b64 v[130:131], 1, v[130:131]
	v_lshl_add_u64 v[176:177], v[150:151], 2, s[8:9]
	v_lshl_add_u64 v[180:181], v[178:179], 0, v[154:155]
	v_lshl_add_u64 v[184:185], v[178:179], 0, v[144:145]
	v_lshl_add_u64 v[178:179], v[178:179], 0, v[130:131]
	s_waitcnt vmcnt(0)
	v_mul_f32_e32 v133, v124, v162
	v_mul_f32_e32 v152, v125, v163
	v_mul_f32_e32 v161, v126, v164
	v_mul_f32_e32 v175, v127, v165
	v_mul_f32_e32 v186, v120, v162
	v_mul_f32_e32 v187, v121, v163
	v_mul_f32_e32 v188, v122, v164
	v_mul_f32_e32 v189, v123, v165
	v_mul_f32_e32 v190, v60, v162
	v_mul_f32_e32 v191, v61, v163
	v_mul_f32_e32 v194, v56, v162
	v_mul_f32_e32 v195, v57, v163
	v_cvt_pk_bf16_f32 v162, v133, v152
	v_cvt_pk_bf16_f32 v163, v161, v175
	v_mul_f32_e32 v192, v62, v164
	v_mul_f32_e32 v193, v63, v165
	v_mul_f32_e32 v196, v58, v164
	v_mul_f32_e32 v197, v59, v165
	v_cvt_pk_bf16_f32 v164, v186, v187
	v_cvt_pk_bf16_f32 v165, v188, v189
	v_cvt_pk_bf16_f32 v186, v190, v191
	v_cvt_pk_bf16_f32 v187, v192, v193
	v_cvt_pk_bf16_f32 v188, v194, v195
	v_cvt_pk_bf16_f32 v189, v196, v197
	global_store_dwordx2 v[182:183], v[162:163], off
	global_store_dwordx2 v[180:181], v[164:165], off
	global_store_dwordx2 v[184:185], v[186:187], off
	global_store_dwordx2 v[178:179], v[188:189], off
	global_load_dwordx4 v[162:165], v[176:177], off
	v_bitop3_b32 v133, v136, 28, 16 bitop3:0xc8
	v_lshlrev_b32_e32 v152, 1, v133
	v_lshl_add_u64 v[178:179], s[12:13], 0, v[252:253]
	v_lshl_add_u64 v[180:181], v[178:179], 0, v[156:157]
	v_lshl_add_u64 v[176:177], v[148:149], 2, s[8:9]
	v_lshl_add_u64 v[182:183], v[178:179], 0, v[154:155]
	v_lshl_add_u64 v[184:185], v[178:179], 0, v[144:145]
	v_lshl_add_u64 v[178:179], v[178:179], 0, v[130:131]
	s_waitcnt vmcnt(0)
	v_mul_f32_e32 v133, v116, v162
	v_mul_f32_e32 v152, v117, v163
	v_mul_f32_e32 v161, v118, v164
	v_mul_f32_e32 v175, v119, v165
	v_mul_f32_e32 v186, v112, v162
	v_mul_f32_e32 v187, v113, v163
	v_mul_f32_e32 v188, v114, v164
	v_mul_f32_e32 v189, v115, v165
	global_load_dwordx4 v[116:119], v[176:177], off
	v_mul_f32_e32 v190, v52, v162
	v_mul_f32_e32 v191, v53, v163
	v_mul_f32_e32 v194, v48, v162
	v_mul_f32_e32 v195, v49, v163
	v_cvt_pk_bf16_f32 v162, v133, v152
	v_cvt_pk_bf16_f32 v163, v161, v175
	v_mul_f32_e32 v192, v54, v164
	v_mul_f32_e32 v193, v55, v165
	v_mul_f32_e32 v196, v50, v164
	v_mul_f32_e32 v197, v51, v165
	v_cvt_pk_bf16_f32 v164, v186, v187
	v_cvt_pk_bf16_f32 v165, v188, v189
	v_cvt_pk_bf16_f32 v186, v190, v191
	v_cvt_pk_bf16_f32 v187, v192, v193
	v_cvt_pk_bf16_f32 v188, v194, v195
	v_cvt_pk_bf16_f32 v189, v196, v197
	global_store_dwordx2 v[180:181], v[162:163], off offset:512
	global_store_dwordx2 v[182:183], v[164:165], off offset:512
	global_store_dwordx2 v[184:185], v[186:187], off offset:512
	global_store_dwordx2 v[178:179], v[188:189], off offset:512
	v_bitop3_b32 v133, v136, 44, 32 bitop3:0xc8
	v_lshlrev_b32_e32 v152, 1, v133
	v_lshl_add_u64 v[178:179], s[12:13], 0, v[252:253]
	v_lshl_add_u64 v[180:181], v[178:179], 0, v[156:157]
	v_lshl_add_u64 v[176:177], v[146:147], 2, s[8:9]
	global_load_dwordx4 v[112:115], v[176:177], off
	v_lshl_add_u64 v[182:183], v[178:179], 0, v[154:155]
	v_lshl_add_u64 v[184:185], v[178:179], 0, v[144:145]
	v_lshl_add_u64 v[178:179], v[178:179], 0, v[130:131]
	s_waitcnt vmcnt(5)
	v_mov_b32_e32 v162, v116
	v_mov_b32_e32 v163, v117
	v_mov_b32_e32 v164, v118
	v_mov_b32_e32 v165, v119
	v_mul_f32_e32 v133, v108, v162
	v_mul_f32_e32 v152, v109, v163
	v_mul_f32_e32 v161, v110, v164
	v_mul_f32_e32 v175, v111, v165
	v_mul_f32_e32 v186, v104, v162
	v_mul_f32_e32 v187, v105, v163
	v_mul_f32_e32 v188, v106, v164
	v_mul_f32_e32 v189, v107, v165
	v_mul_f32_e32 v190, v44, v162
	v_mul_f32_e32 v191, v45, v163
	v_mul_f32_e32 v194, v40, v162
	v_mul_f32_e32 v195, v41, v163
	v_cvt_pk_bf16_f32 v162, v133, v152
	v_cvt_pk_bf16_f32 v163, v161, v175
	v_mul_f32_e32 v192, v46, v164
	v_mul_f32_e32 v193, v47, v165
	v_mul_f32_e32 v196, v42, v164
	v_mul_f32_e32 v197, v43, v165
	v_cvt_pk_bf16_f32 v164, v186, v187
	v_cvt_pk_bf16_f32 v165, v188, v189
	v_cvt_pk_bf16_f32 v186, v190, v191
	v_cvt_pk_bf16_f32 v187, v192, v193
	v_cvt_pk_bf16_f32 v188, v194, v195
	v_cvt_pk_bf16_f32 v189, v196, v197
	global_store_dwordx2 v[180:181], v[162:163], off offset:1024
	global_store_dwordx2 v[182:183], v[164:165], off offset:1024
	global_store_dwordx2 v[184:185], v[186:187], off offset:1024
	global_store_dwordx2 v[178:179], v[188:189], off offset:1024
	v_bitop3_b32 v133, v136, 60, 48 bitop3:0xc8
	v_lshlrev_b32_e32 v152, 1, v133
	v_lshl_add_u64 v[178:179], s[12:13], 0, v[252:253]
	v_lshl_add_u64 v[180:181], v[178:179], 0, v[156:157]
	v_lshl_add_u64 v[176:177], v[142:143], 2, s[8:9]
	global_load_dwordx4 v[116:119], v[176:177], off
	v_lshl_add_u64 v[182:183], v[178:179], 0, v[154:155]
	v_lshl_add_u64 v[184:185], v[178:179], 0, v[144:145]
	v_lshl_add_u64 v[178:179], v[178:179], 0, v[130:131]
	s_waitcnt vmcnt(5)
	v_mov_b32_e32 v162, v112
	v_mov_b32_e32 v163, v113
	v_mov_b32_e32 v164, v114
	v_mov_b32_e32 v165, v115
	v_mul_f32_e32 v133, v100, v162
	v_mul_f32_e32 v152, v101, v163
	v_mul_f32_e32 v161, v102, v164
	v_mul_f32_e32 v175, v103, v165
	v_mul_f32_e32 v186, v96, v162
	v_mul_f32_e32 v187, v97, v163
	v_mul_f32_e32 v188, v98, v164
	v_mul_f32_e32 v189, v99, v165
	v_mul_f32_e32 v190, v36, v162
	v_mul_f32_e32 v191, v37, v163
	v_mul_f32_e32 v194, v32, v162
	v_mul_f32_e32 v195, v33, v163
	v_cvt_pk_bf16_f32 v162, v133, v152
	v_cvt_pk_bf16_f32 v163, v161, v175
	v_mul_f32_e32 v192, v38, v164
	v_mul_f32_e32 v193, v39, v165
	v_mul_f32_e32 v196, v34, v164
	v_mul_f32_e32 v197, v35, v165
	v_cvt_pk_bf16_f32 v164, v186, v187
	v_cvt_pk_bf16_f32 v165, v188, v189
	v_cvt_pk_bf16_f32 v186, v190, v191
	v_cvt_pk_bf16_f32 v187, v192, v193
	v_cvt_pk_bf16_f32 v188, v194, v195
	v_cvt_pk_bf16_f32 v189, v196, v197
	global_store_dwordx2 v[180:181], v[162:163], off offset:1536
	global_store_dwordx2 v[182:183], v[164:165], off offset:1536
	global_store_dwordx2 v[184:185], v[186:187], off offset:1536
	global_store_dwordx2 v[178:179], v[188:189], off offset:1536
	v_bitop3_b32 v133, v136, s39, 64 bitop3:0xc8
	v_lshlrev_b32_e32 v152, 1, v133
	v_lshl_add_u64 v[178:179], s[12:13], 0, v[252:253]
	v_lshl_add_u64 v[180:181], v[178:179], 0, v[156:157]
	v_lshl_add_u64 v[176:177], v[140:141], 2, s[8:9]
	global_load_dwordx4 v[112:115], v[176:177], off
	v_lshl_add_u64 v[182:183], v[178:179], 0, v[154:155]
	v_lshl_add_u64 v[184:185], v[178:179], 0, v[144:145]
	v_lshl_add_u64 v[178:179], v[178:179], 0, v[130:131]
	s_waitcnt vmcnt(5)
	v_mov_b32_e32 v162, v116
	v_mov_b32_e32 v163, v117
	v_mov_b32_e32 v164, v118
	v_mov_b32_e32 v165, v119
	v_mul_f32_e32 v133, v92, v162
	v_mul_f32_e32 v152, v93, v163
	v_mul_f32_e32 v161, v94, v164
	v_mul_f32_e32 v175, v95, v165
	v_mul_f32_e32 v186, v88, v162
	v_mul_f32_e32 v187, v89, v163
	v_mul_f32_e32 v188, v90, v164
	v_mul_f32_e32 v189, v91, v165
	v_mul_f32_e32 v190, v28, v162
	v_mul_f32_e32 v191, v29, v163
	v_mul_f32_e32 v194, v24, v162
	v_mul_f32_e32 v195, v25, v163
	v_cvt_pk_bf16_f32 v162, v133, v152
	v_cvt_pk_bf16_f32 v163, v161, v175
	v_mul_f32_e32 v192, v30, v164
	v_mul_f32_e32 v193, v31, v165
	v_mul_f32_e32 v196, v26, v164
	v_mul_f32_e32 v197, v27, v165
	v_cvt_pk_bf16_f32 v164, v186, v187
	v_cvt_pk_bf16_f32 v165, v188, v189
	v_cvt_pk_bf16_f32 v186, v190, v191
	v_cvt_pk_bf16_f32 v187, v192, v193
	v_cvt_pk_bf16_f32 v188, v194, v195
	v_cvt_pk_bf16_f32 v189, v196, v197
	global_store_dwordx2 v[180:181], v[162:163], off offset:2048
	global_store_dwordx2 v[182:183], v[164:165], off offset:2048
	global_store_dwordx2 v[184:185], v[186:187], off offset:2048
	global_store_dwordx2 v[178:179], v[188:189], off offset:2048
	v_bitop3_b32 v133, v136, s40, v166 bitop3:0xc8
	v_lshlrev_b32_e32 v152, 1, v133
	v_lshl_add_u64 v[178:179], s[12:13], 0, v[252:253]
	v_lshl_add_u64 v[180:181], v[178:179], 0, v[156:157]
	v_lshl_add_u64 v[176:177], v[138:139], 2, s[8:9]
	global_load_dwordx4 v[116:119], v[176:177], off
	v_lshl_add_u64 v[182:183], v[178:179], 0, v[154:155]
	v_lshl_add_u64 v[184:185], v[178:179], 0, v[144:145]
	v_lshl_add_u64 v[178:179], v[178:179], 0, v[130:131]
	s_waitcnt vmcnt(5)
	v_mov_b32_e32 v162, v112
	v_mov_b32_e32 v163, v113
	v_mov_b32_e32 v164, v114
	v_mov_b32_e32 v165, v115
	v_mul_f32_e32 v133, v84, v162
	v_mul_f32_e32 v152, v85, v163
	v_mul_f32_e32 v161, v86, v164
	v_mul_f32_e32 v175, v87, v165
	v_mul_f32_e32 v186, v80, v162
	v_mul_f32_e32 v187, v81, v163
	v_mul_f32_e32 v188, v82, v164
	v_mul_f32_e32 v189, v83, v165
	v_mul_f32_e32 v190, v20, v162
	v_mul_f32_e32 v191, v21, v163
	v_mul_f32_e32 v194, v16, v162
	v_mul_f32_e32 v195, v17, v163
	v_cvt_pk_bf16_f32 v162, v133, v152
	v_cvt_pk_bf16_f32 v163, v161, v175
	v_mul_f32_e32 v192, v22, v164
	v_mul_f32_e32 v193, v23, v165
	v_mul_f32_e32 v196, v18, v164
	v_mul_f32_e32 v197, v19, v165
	v_cvt_pk_bf16_f32 v164, v186, v187
	v_cvt_pk_bf16_f32 v165, v188, v189
	v_cvt_pk_bf16_f32 v186, v190, v191
	v_cvt_pk_bf16_f32 v187, v192, v193
	v_cvt_pk_bf16_f32 v188, v194, v195
	v_cvt_pk_bf16_f32 v189, v196, v197
	global_store_dwordx2 v[180:181], v[162:163], off offset:2560
	global_store_dwordx2 v[182:183], v[164:165], off offset:2560
	global_store_dwordx2 v[184:185], v[186:187], off offset:2560
	global_store_dwordx2 v[178:179], v[188:189], off offset:2560
	v_bitop3_b32 v133, v136, s41, v167 bitop3:0xc8
	v_lshlrev_b32_e32 v152, 1, v133
	v_lshl_add_u64 v[178:179], s[12:13], 0, v[252:253]
	v_lshl_add_u64 v[180:181], v[178:179], 0, v[156:157]
	v_lshl_add_u64 v[176:177], v[134:135], 2, s[8:9]
	global_load_dwordx4 v[112:115], v[176:177], off
	v_lshl_add_u64 v[182:183], v[178:179], 0, v[154:155]
	v_lshl_add_u64 v[184:185], v[178:179], 0, v[144:145]
	v_lshl_add_u64 v[178:179], v[178:179], 0, v[130:131]
	s_waitcnt vmcnt(5)
	v_mov_b32_e32 v162, v116
	v_mov_b32_e32 v163, v117
	v_mov_b32_e32 v164, v118
	v_mov_b32_e32 v165, v119
	v_mul_f32_e32 v133, v76, v162
	v_mul_f32_e32 v152, v77, v163
	v_mul_f32_e32 v161, v78, v164
	v_mul_f32_e32 v175, v79, v165
	v_mul_f32_e32 v186, v72, v162
	v_mul_f32_e32 v187, v73, v163
	v_mul_f32_e32 v188, v74, v164
	v_mul_f32_e32 v189, v75, v165
	v_mul_f32_e32 v190, v12, v162
	v_mul_f32_e32 v191, v13, v163
	v_mul_f32_e32 v194, v8, v162
	v_mul_f32_e32 v195, v9, v163
	v_cvt_pk_bf16_f32 v162, v133, v152
	v_cvt_pk_bf16_f32 v163, v161, v175
	v_mul_f32_e32 v192, v14, v164
	v_mul_f32_e32 v193, v15, v165
	v_mul_f32_e32 v196, v10, v164
	v_mul_f32_e32 v197, v11, v165
	v_cvt_pk_bf16_f32 v164, v186, v187
	v_cvt_pk_bf16_f32 v165, v188, v189
	v_cvt_pk_bf16_f32 v186, v190, v191
	v_cvt_pk_bf16_f32 v187, v192, v193
	v_cvt_pk_bf16_f32 v188, v194, v195
	v_cvt_pk_bf16_f32 v189, v196, v197
	global_store_dwordx2 v[180:181], v[162:163], off offset:3072
	global_store_dwordx2 v[182:183], v[164:165], off offset:3072
	global_store_dwordx2 v[184:185], v[186:187], off offset:3072
	global_store_dwordx2 v[178:179], v[188:189], off offset:3072
	v_bitop3_b32 v133, v136, s42, v168 bitop3:0xc8
	v_lshlrev_b32_e32 v152, 1, v133
	v_lshl_add_u64 v[176:177], s[12:13], 0, v[252:253]
	v_lshl_add_u64 v[156:157], v[176:177], 0, v[156:157]
	v_lshl_add_u64 v[154:155], v[176:177], 0, v[154:155]
	v_lshl_add_u64 v[144:145], v[176:177], 0, v[144:145]
	v_lshl_add_u64 v[130:131], v[176:177], 0, v[130:131]
	s_waitcnt vmcnt(4)
	v_mov_b32_e32 v162, v112
	v_mov_b32_e32 v163, v113
	v_mov_b32_e32 v164, v114
	v_mov_b32_e32 v165, v115
	v_mul_f32_e32 v133, v68, v162
	v_mul_f32_e32 v152, v69, v163
	v_mul_f32_e32 v161, v70, v164
	v_mul_f32_e32 v175, v71, v165
	v_mul_f32_e32 v176, v64, v162
	v_mul_f32_e32 v177, v65, v163
	v_mul_f32_e32 v178, v66, v164
	v_mul_f32_e32 v179, v67, v165
	v_mul_f32_e32 v180, v4, v162
	v_mul_f32_e32 v181, v5, v163
	v_mul_f32_e32 v184, v0, v162
	v_mul_f32_e32 v185, v1, v163
	v_cvt_pk_bf16_f32 v162, v133, v152
	v_cvt_pk_bf16_f32 v163, v161, v175
	v_mul_f32_e32 v182, v6, v164
	v_mul_f32_e32 v183, v7, v165
	v_mul_f32_e32 v186, v2, v164
	v_mul_f32_e32 v187, v3, v165
	v_cvt_pk_bf16_f32 v164, v176, v177
	v_cvt_pk_bf16_f32 v165, v178, v179
	v_cvt_pk_bf16_f32 v176, v180, v181
	v_cvt_pk_bf16_f32 v177, v182, v183
	v_cvt_pk_bf16_f32 v178, v184, v185
	v_cvt_pk_bf16_f32 v179, v186, v187
	global_store_dwordx2 v[156:157], v[162:163], off offset:3584
	global_store_dwordx2 v[154:155], v[164:165], off offset:3584
	global_store_dwordx2 v[144:145], v[176:177], off offset:3584
	global_store_dwordx2 v[130:131], v[178:179], off offset:3584
	s_cbranch_execnz .LBB0_206
	s_branch .LBB0_212

.LBB0_710:
	s_add_i32 s11, s10, 64
	s_min_u32 s13, s11, 0x3e0
	s_lshl_b32 s16, s13, 1
	v_lshl_add_u64 v[172:173], v[154:155], 0, s[16:17]
	v_lshl_add_u64 v[176:177], v[158:159], 0, s[16:17]
	v_lshl_add_u64 v[180:181], v[160:161], 0, s[16:17]
	v_lshl_add_u64 v[184:185], v[162:163], 0, s[16:17]
	v_lshl_add_u64 v[188:189], v[156:157], 0, s[16:17]
	v_lshl_add_u64 v[192:193], v[164:165], 0, s[16:17]
	global_load_dwordx4 v[172:175], v[172:173], off
	ds_read_b128 v[196:199], v171 offset:32768
	global_load_dwordx4 v[176:179], v[176:177], off
	ds_read_b128 v[200:203], v171 offset:33792
	global_load_dwordx4 v[180:183], v[180:181], off
	ds_read_b128 v[204:207], v171 offset:34816
	global_load_dwordx4 v[184:187], v[184:185], off
	ds_read_b128 v[208:211], v171 offset:35840
	global_load_dwordx4 v[188:191], v[188:189], off
	ds_read_b128 v[212:215], v169
	global_load_dwordx4 v[192:195], v[192:193], off
	ds_read_b128 v[216:219], v169 offset:1024
	ds_read_b128 v[222:225], v169 offset:2048
	ds_read_b128 v[226:229], v169 offset:3072
	ds_read_b128 v[230:233], v169 offset:4096
	ds_read_b128 v[234:237], v169 offset:5120
	ds_read_b128 v[238:241], v169 offset:6144
	ds_read_b128 v[242:245], v169 offset:7168
	s_setprio 1
	s_waitcnt lgkmcnt(7)
	v_mfma_f32_16x16x32_bf16 v[148:151], v[212:215], v[196:199], v[148:151]
	v_mfma_f32_16x16x32_bf16 v[144:147], v[212:215], v[200:203], v[144:147]
	v_mfma_f32_16x16x32_bf16 v[140:143], v[212:215], v[204:207], v[140:143]
	v_mfma_f32_16x16x32_bf16 v[128:131], v[212:215], v[208:211], v[128:131]
	s_waitcnt vmcnt(11)
	ds_write_b128 v152, v[112:115] offset:16384
	s_waitcnt lgkmcnt(7)
	v_mfma_f32_16x16x32_bf16 v[108:111], v[216:219], v[196:199], v[108:111]
	v_mfma_f32_16x16x32_bf16 v[104:107], v[216:219], v[200:203], v[104:107]
	v_mfma_f32_16x16x32_bf16 v[100:103], v[216:219], v[204:207], v[100:103]
	v_mfma_f32_16x16x32_bf16 v[96:99], v[216:219], v[208:211], v[96:99]
	s_waitcnt vmcnt(9)
	ds_write_b128 v152, v[120:123] offset:20480
	s_waitcnt lgkmcnt(7)
	v_mfma_f32_16x16x32_bf16 v[92:95], v[222:225], v[196:199], v[92:95]
	v_mfma_f32_16x16x32_bf16 v[88:91], v[222:225], v[200:203], v[88:91]
	v_mfma_f32_16x16x32_bf16 v[84:87], v[222:225], v[204:207], v[84:87]
	v_mfma_f32_16x16x32_bf16 v[80:83], v[222:225], v[208:211], v[80:83]
	s_waitcnt vmcnt(8)
	ds_write_b128 v152, v[124:127] offset:24576
	s_waitcnt lgkmcnt(7)
	v_mfma_f32_16x16x32_bf16 v[76:79], v[226:229], v[196:199], v[76:79]
	v_mfma_f32_16x16x32_bf16 v[72:75], v[226:229], v[200:203], v[72:75]
	v_mfma_f32_16x16x32_bf16 v[68:71], v[226:229], v[204:207], v[68:71]
	v_mfma_f32_16x16x32_bf16 v[64:67], v[226:229], v[208:211], v[64:67]
	s_waitcnt vmcnt(7)
	ds_write_b128 v152, v[132:135] offset:28672
	s_waitcnt lgkmcnt(7)
	v_mfma_f32_16x16x32_bf16 v[60:63], v[230:233], v[196:199], v[60:63]
	v_mfma_f32_16x16x32_bf16 v[56:59], v[230:233], v[200:203], v[56:59]
	v_mfma_f32_16x16x32_bf16 v[52:55], v[230:233], v[204:207], v[52:55]
	v_mfma_f32_16x16x32_bf16 v[48:51], v[230:233], v[208:211], v[48:51]
	s_waitcnt vmcnt(7)
	ds_write_b128 v152, v[116:119] offset:40960
	s_waitcnt lgkmcnt(7)
	v_mfma_f32_16x16x32_bf16 v[44:47], v[234:237], v[196:199], v[44:47]
	v_mfma_f32_16x16x32_bf16 v[40:43], v[234:237], v[200:203], v[40:43]
	v_mfma_f32_16x16x32_bf16 v[36:39], v[234:237], v[204:207], v[36:39]
	v_mfma_f32_16x16x32_bf16 v[32:35], v[234:237], v[208:211], v[32:35]
	s_waitcnt vmcnt(6)
	ds_write_b128 v152, v[136:139] offset:45056
	s_waitcnt lgkmcnt(7)
	v_mfma_f32_16x16x32_bf16 v[28:31], v[238:241], v[196:199], v[28:31]
	v_mfma_f32_16x16x32_bf16 v[24:27], v[238:241], v[200:203], v[24:27]
	v_mfma_f32_16x16x32_bf16 v[20:23], v[238:241], v[204:207], v[20:23]
	v_mfma_f32_16x16x32_bf16 v[16:19], v[238:241], v[208:211], v[16:19]
	s_waitcnt lgkmcnt(6)
	v_mfma_f32_16x16x32_bf16 v[12:15], v[242:245], v[196:199], v[12:15]
	v_mfma_f32_16x16x32_bf16 v[8:11], v[242:245], v[200:203], v[8:11]
	v_mfma_f32_16x16x32_bf16 v[4:7], v[242:245], v[204:207], v[4:7]
	v_mfma_f32_16x16x32_bf16 v[0:3], v[242:245], v[208:211], v[0:3]
	s_setprio 0
	s_min_u32 s10, s10, 0x380
	s_lshl_b32 s16, s10, 1
	s_mov_b32 s27, s17
	s_add_i32 s26, s16, 0xc0
	v_lshl_add_u64 v[112:113], v[154:155], 0, s[16:17]
	v_lshl_add_u64 v[116:117], v[156:157], 0, s[16:17]
	v_lshl_add_u64 v[120:121], v[158:159], 0, s[26:27]
	v_lshl_add_u64 v[124:125], v[160:161], 0, s[26:27]
	v_lshl_add_u64 v[132:133], v[162:163], 0, s[26:27]
	v_lshl_add_u64 v[136:137], v[164:165], 0, s[26:27]
	s_waitcnt lgkmcnt(0)
	s_barrier
	global_load_dwordx4 v[112:115], v[112:113], off offset:192
	ds_read_b128 v[196:199], v168 offset:40960
	global_load_dwordx4 v[116:119], v[116:117], off offset:192
	ds_read_b128 v[200:203], v168 offset:41984
	global_load_dwordx4 v[120:123], v[120:121], off
	ds_read_b128 v[204:207], v168 offset:43008
	global_load_dwordx4 v[124:127], v[124:125], off
	ds_read_b128 v[208:211], v168 offset:44032
	global_load_dwordx4 v[132:135], v[132:133], off
	ds_read_b128 v[212:215], v170
	global_load_dwordx4 v[136:139], v[136:137], off
	ds_read_b128 v[216:219], v170 offset:1024
	ds_read_b128 v[222:225], v170 offset:2048
	ds_read_b128 v[226:229], v170 offset:3072
	ds_read_b128 v[230:233], v170 offset:4096
	ds_read_b128 v[234:237], v170 offset:5120
	ds_read_b128 v[238:241], v170 offset:6144
	ds_read_b128 v[242:245], v170 offset:7168
	s_setprio 1
	s_waitcnt lgkmcnt(7)
	v_mfma_f32_16x16x32_bf16 v[148:151], v[212:215], v[196:199], v[148:151]
	v_mfma_f32_16x16x32_bf16 v[144:147], v[212:215], v[200:203], v[144:147]
	v_mfma_f32_16x16x32_bf16 v[140:143], v[212:215], v[204:207], v[140:143]
	v_mfma_f32_16x16x32_bf16 v[128:131], v[212:215], v[208:211], v[128:131]
	s_waitcnt vmcnt(11)
	ds_write_b128 v152, v[172:175]
	s_waitcnt lgkmcnt(7)
	v_mfma_f32_16x16x32_bf16 v[108:111], v[216:219], v[196:199], v[108:111]
	v_mfma_f32_16x16x32_bf16 v[104:107], v[216:219], v[200:203], v[104:107]
	v_mfma_f32_16x16x32_bf16 v[100:103], v[216:219], v[204:207], v[100:103]
	v_mfma_f32_16x16x32_bf16 v[96:99], v[216:219], v[208:211], v[96:99]
	s_waitcnt vmcnt(10)
	ds_write_b128 v152, v[176:179] offset:4096
	s_waitcnt lgkmcnt(7)
	v_mfma_f32_16x16x32_bf16 v[92:95], v[222:225], v[196:199], v[92:95]
	v_mfma_f32_16x16x32_bf16 v[88:91], v[222:225], v[200:203], v[88:91]
	v_mfma_f32_16x16x32_bf16 v[84:87], v[222:225], v[204:207], v[84:87]
	v_mfma_f32_16x16x32_bf16 v[80:83], v[222:225], v[208:211], v[80:83]
	s_waitcnt vmcnt(9)
	ds_write_b128 v152, v[180:183] offset:8192
	s_waitcnt lgkmcnt(7)
	v_mfma_f32_16x16x32_bf16 v[76:79], v[226:229], v[196:199], v[76:79]
	v_mfma_f32_16x16x32_bf16 v[72:75], v[226:229], v[200:203], v[72:75]
	v_mfma_f32_16x16x32_bf16 v[68:71], v[226:229], v[204:207], v[68:71]
	v_mfma_f32_16x16x32_bf16 v[64:67], v[226:229], v[208:211], v[64:67]
	s_waitcnt vmcnt(8)
	ds_write_b128 v152, v[184:187] offset:12288
	s_waitcnt lgkmcnt(7)
	v_mfma_f32_16x16x32_bf16 v[60:63], v[230:233], v[196:199], v[60:63]
	v_mfma_f32_16x16x32_bf16 v[56:59], v[230:233], v[200:203], v[56:59]
	v_mfma_f32_16x16x32_bf16 v[52:55], v[230:233], v[204:207], v[52:55]
	v_mfma_f32_16x16x32_bf16 v[48:51], v[230:233], v[208:211], v[48:51]
	s_waitcnt vmcnt(7)
	ds_write_b128 v152, v[188:191] offset:32768
	s_waitcnt lgkmcnt(7)
	v_mfma_f32_16x16x32_bf16 v[44:47], v[234:237], v[196:199], v[44:47]
	v_mfma_f32_16x16x32_bf16 v[40:43], v[234:237], v[200:203], v[40:43]
	v_mfma_f32_16x16x32_bf16 v[36:39], v[234:237], v[204:207], v[36:39]
	v_mfma_f32_16x16x32_bf16 v[32:35], v[234:237], v[208:211], v[32:35]
	s_waitcnt vmcnt(6)
	ds_write_b128 v152, v[192:195] offset:36864
	s_waitcnt lgkmcnt(7)
	v_mfma_f32_16x16x32_bf16 v[28:31], v[238:241], v[196:199], v[28:31]
	v_mfma_f32_16x16x32_bf16 v[24:27], v[238:241], v[200:203], v[24:27]
	v_mfma_f32_16x16x32_bf16 v[20:23], v[238:241], v[204:207], v[20:23]
	v_mfma_f32_16x16x32_bf16 v[16:19], v[238:241], v[208:211], v[16:19]
	s_waitcnt lgkmcnt(6)
	v_mfma_f32_16x16x32_bf16 v[12:15], v[242:245], v[196:199], v[12:15]
	v_mfma_f32_16x16x32_bf16 v[8:11], v[242:245], v[200:203], v[8:11]
	v_mfma_f32_16x16x32_bf16 v[4:7], v[242:245], v[204:207], v[4:7]
	v_mfma_f32_16x16x32_bf16 v[0:3], v[242:245], v[208:211], v[0:3]
	s_setprio 0
	s_add_i32 s1, s1, 2
	s_cmp_lt_u32 s1, 30
	s_mov_b32 s10, s11
	s_waitcnt lgkmcnt(0)
	s_barrier
	s_cbranch_scc1 .LBB0_710
	s_waitcnt vmcnt(5)
	v_mov_b32_e32 v114, v220
	v_mov_b32_e32 v115, v153
	v_and_b32_e32 v112, 0xffffff80, v114
	s_waitcnt vmcnt(4)
	v_add_u32_e32 v116, s0, v112
	v_lshrrev_b32_e32 v112, 2, v114
	v_and_b32_e32 v118, 12, v112
	s_waitcnt vmcnt(3)
	v_or_b32_e32 v120, v118, v116
	v_ashrrev_i32_e32 v121, 31, v120
	v_lshl_add_u64 v[112:113], v[120:121], 2, s[14:15]
	global_load_dwordx4 v[132:135], v[112:113], off
	v_ashrrev_i32_e32 v122, 14, v116
	v_ashrrev_i32_e32 v123, 31, v122
	v_lshlrev_b64 v[122:123], 10, v[122:123]
	v_mov_b64_e32 v[112:113], s[34:35]
	s_waitcnt vmcnt(3)
	v_lshrrev_b32_e32 v126, 6, v116
	v_or_b32_e32 v124, 16, v120
	v_lshl_or_b32 v121, s12, 8, v122
	v_ashrrev_i32_e32 v125, 31, v124
	v_and_or_b32 v122, v126, s49, v121
	s_waitcnt vmcnt(1)
	v_lshl_add_u64 v[136:137], v[124:125], 2, s[14:15]
	global_load_dwordx4 v[246:249], v[136:137], off
	v_lshlrev_b64 v[124:125], 14, v[122:123]
	v_lshlrev_b32_e32 v114, 7, v114
	v_lshlrev_b32_e32 v152, 1, v118
	v_lshl_add_u64 v[124:125], s[38:39], 0, v[124:125]
	v_and_b32_e32 v114, 0x2780, v114
	v_lshl_add_u64 v[126:127], v[124:125], 0, v[152:153]
	v_mov_b32_e32 v117, v153
	v_mov_b32_e32 v119, v153
	v_or_b32_e32 v116, 0x1000, v114
	v_or_b32_e32 v118, 0x1800, v114
	v_lshl_add_u64 v[124:125], v[126:127], 0, v[114:115]
	v_lshl_add_u64 v[138:139], v[126:127], 0, v[116:117]
	v_lshl_add_u64 v[154:155], v[126:127], 0, v[118:119]
	s_waitcnt vmcnt(1)
	v_pk_fma_f32 v[132:133], v[132:133], s[30:31], v[112:113] op_sel_hi:[1,0,0]
	v_pk_fma_f32 v[134:135], v[134:135], s[30:31], v[112:113] op_sel_hi:[1,0,0]
	v_mul_f32_e32 v122, 0x4b800000, v132
	v_mul_f32_e32 v156, 0x4b800000, v133
	v_mul_f32_e32 v157, 0x4b800000, v134
	v_mul_f32_e32 v158, 0x4b800000, v135
	v_cmp_gt_f32_e32 vcc, s40, v132
	v_cmp_gt_f32_e64 s[0:1], s40, v133
	v_cmp_gt_f32_e64 s[10:11], s40, v134
	v_cmp_gt_f32_e64 s[12:13], s40, v135
	v_cndmask_b32_e32 v122, v132, v122, vcc
	v_cndmask_b32_e64 v132, v133, v156, s[0:1]
	v_cndmask_b32_e64 v133, v134, v157, s[10:11]
	v_cndmask_b32_e64 v134, v135, v158, s[12:13]
	v_rsq_f32_e32 v122, v122
	v_rsq_f32_e32 v132, v132
	v_rsq_f32_e32 v133, v133
	v_rsq_f32_e32 v134, v134
	v_mul_f32_e32 v135, 0x45800000, v122
	v_mul_f32_e32 v156, 0x45800000, v132
	v_mul_f32_e32 v157, 0x45800000, v133
	v_mul_f32_e32 v158, 0x45800000, v134
	v_cndmask_b32_e32 v122, v122, v135, vcc
	v_cndmask_b32_e64 v132, v132, v156, s[0:1]
	v_cndmask_b32_e64 v133, v133, v157, s[10:11]
	v_cndmask_b32_e64 v134, v134, v158, s[12:13]
	v_mul_f32_e32 v135, v148, v122
	v_mul_f32_e32 v148, v149, v132
	v_mul_f32_e32 v149, v150, v133
	v_mul_f32_e32 v150, v151, v134
	v_mul_f32_e32 v144, v144, v122
	v_mul_f32_e32 v140, v140, v122
	v_mul_f32_e32 v122, v128, v122
	v_mul_f32_e32 v151, v129, v132
	v_cvt_pk_bf16_f32 v128, v135, v148
	v_cvt_pk_bf16_f32 v129, v149, v150
	v_mul_f32_e32 v145, v145, v132
	v_mul_f32_e32 v146, v146, v133
	v_mul_f32_e32 v147, v147, v134
	v_mul_f32_e32 v141, v141, v132
	v_mul_f32_e32 v142, v142, v133
	v_mul_f32_e32 v143, v143, v134
	v_mul_f32_e32 v156, v130, v133
	v_mul_f32_e32 v157, v131, v134
	v_cvt_pk_bf16_f32 v130, v144, v145
	v_cvt_pk_bf16_f32 v131, v146, v147
	v_cvt_pk_bf16_f32 v132, v140, v141
	v_cvt_pk_bf16_f32 v133, v142, v143
	v_cvt_pk_bf16_f32 v134, v122, v151
	v_cvt_pk_bf16_f32 v135, v156, v157
	global_store_dwordx2 v[124:125], v[128:129], off
	global_store_dwordx2 v[124:125], v[130:131], off offset:2048
	global_store_dwordx2 v[138:139], v[132:133], off
	global_store_dwordx2 v[154:155], v[134:135], off
	v_or_b32_e32 v132, 32, v120
	v_ashrrev_i32_e32 v133, 31, v132
	v_lshl_add_u64 v[134:135], v[126:127], 0, 32
	v_lshl_add_u64 v[132:133], v[132:133], 2, s[14:15]
	global_load_dwordx4 v[250:253], v[132:133], off
	v_lshl_add_u64 v[136:137], v[134:135], 0, v[116:117]
	v_lshl_add_u64 v[134:135], v[134:135], 0, v[118:119]
	s_waitcnt vmcnt(5)
	v_mov_b32_e32 v128, v246
	v_mov_b32_e32 v129, v247
	v_mov_b32_e32 v130, v248
	v_mov_b32_e32 v131, v249
	v_pk_fma_f32 v[128:129], v[128:129], s[30:31], v[112:113] op_sel_hi:[1,0,0]
	v_pk_fma_f32 v[130:131], v[130:131], s[30:31], v[112:113] op_sel_hi:[1,0,0]
	v_mul_f32_e32 v122, 0x4b800000, v128
	v_mul_f32_e32 v138, 0x4b800000, v129
	v_mul_f32_e32 v139, 0x4b800000, v130
	v_mul_f32_e32 v140, 0x4b800000, v131
	v_cmp_gt_f32_e32 vcc, s40, v128
	v_cmp_gt_f32_e64 s[0:1], s40, v129
	v_cmp_gt_f32_e64 s[10:11], s40, v130
	v_cmp_gt_f32_e64 s[12:13], s40, v131
	v_cndmask_b32_e32 v122, v128, v122, vcc
	v_cndmask_b32_e64 v128, v129, v138, s[0:1]
	v_cndmask_b32_e64 v129, v130, v139, s[10:11]
	v_cndmask_b32_e64 v130, v131, v140, s[12:13]
	v_rsq_f32_e32 v122, v122
	v_rsq_f32_e32 v128, v128
	v_rsq_f32_e32 v129, v129
	v_rsq_f32_e32 v130, v130
	v_mul_f32_e32 v131, 0x45800000, v122
	v_mul_f32_e32 v138, 0x45800000, v128
	v_mul_f32_e32 v139, 0x45800000, v129
	v_mul_f32_e32 v140, 0x45800000, v130
	v_cndmask_b32_e32 v122, v122, v131, vcc
	v_cndmask_b32_e64 v128, v128, v138, s[0:1]
	v_cndmask_b32_e64 v129, v129, v139, s[10:11]
	v_cndmask_b32_e64 v130, v130, v140, s[12:13]
	v_mul_f32_e32 v108, v108, v122
	v_mul_f32_e32 v109, v109, v128
	v_mul_f32_e32 v110, v110, v129
	v_mul_f32_e32 v111, v111, v130
	v_mul_f32_e32 v104, v104, v122
	v_mul_f32_e32 v105, v105, v128
	v_mul_f32_e32 v100, v100, v122
	v_mul_f32_e32 v101, v101, v128
	v_mul_f32_e32 v102, v102, v129
	v_mul_f32_e32 v103, v103, v130
	v_mul_f32_e32 v122, v96, v122
	v_mul_f32_e32 v128, v97, v128
	v_cvt_pk_bf16_f32 v96, v108, v109
	v_cvt_pk_bf16_f32 v97, v110, v111
	v_mul_f32_e32 v106, v106, v129
	v_mul_f32_e32 v107, v107, v130
	v_mul_f32_e32 v129, v98, v129
	v_mul_f32_e32 v130, v99, v130
	v_cvt_pk_bf16_f32 v98, v104, v105
	v_cvt_pk_bf16_f32 v99, v106, v107
	v_cvt_pk_bf16_f32 v100, v100, v101
	v_cvt_pk_bf16_f32 v101, v102, v103
	v_cvt_pk_bf16_f32 v102, v122, v128
	v_cvt_pk_bf16_f32 v103, v129, v130
	global_store_dwordx2 v[124:125], v[96:97], off offset:32
	global_store_dwordx2 v[124:125], v[98:99], off offset:2080
	global_store_dwordx2 v[136:137], v[100:101], off
	global_store_dwordx2 v[134:135], v[102:103], off
	v_or_b32_e32 v100, 48, v120
	v_ashrrev_i32_e32 v101, 31, v100
	v_lshl_add_u64 v[102:103], v[126:127], 0, 64
	v_lshl_add_u64 v[100:101], v[100:101], 2, s[14:15]
	global_load_dwordx4 v[246:249], v[100:101], off
	v_lshl_add_u64 v[104:105], v[102:103], 0, v[116:117]
	v_lshl_add_u64 v[102:103], v[102:103], 0, v[118:119]
	s_waitcnt vmcnt(5)
	v_mov_b32_e32 v96, v250
	v_mov_b32_e32 v97, v251
	v_mov_b32_e32 v98, v252
	v_mov_b32_e32 v99, v253
	v_pk_fma_f32 v[96:97], v[96:97], s[30:31], v[112:113] op_sel_hi:[1,0,0]
	v_pk_fma_f32 v[98:99], v[98:99], s[30:31], v[112:113] op_sel_hi:[1,0,0]
	v_mul_f32_e32 v106, 0x4b800000, v96
	v_mul_f32_e32 v107, 0x4b800000, v97
	v_mul_f32_e32 v108, 0x4b800000, v98
	v_mul_f32_e32 v109, 0x4b800000, v99
	v_cmp_gt_f32_e32 vcc, s40, v96
	v_cmp_gt_f32_e64 s[0:1], s40, v97
	v_cmp_gt_f32_e64 s[10:11], s40, v98
	v_cmp_gt_f32_e64 s[12:13], s40, v99
	v_cndmask_b32_e32 v96, v96, v106, vcc
	v_cndmask_b32_e64 v97, v97, v107, s[0:1]
	v_cndmask_b32_e64 v98, v98, v108, s[10:11]
	v_cndmask_b32_e64 v99, v99, v109, s[12:13]
	v_rsq_f32_e32 v96, v96
	v_rsq_f32_e32 v97, v97
	v_rsq_f32_e32 v98, v98
	v_rsq_f32_e32 v99, v99
	v_mul_f32_e32 v106, 0x45800000, v96
	v_mul_f32_e32 v107, 0x45800000, v97
	v_mul_f32_e32 v108, 0x45800000, v98
	v_mul_f32_e32 v109, 0x45800000, v99
	v_cndmask_b32_e32 v96, v96, v106, vcc
	v_cndmask_b32_e64 v97, v97, v107, s[0:1]
	v_cndmask_b32_e64 v98, v98, v108, s[10:11]
	v_cndmask_b32_e64 v99, v99, v109, s[12:13]
	v_mul_f32_e32 v92, v92, v96
	v_mul_f32_e32 v93, v93, v97
	v_mul_f32_e32 v94, v94, v98
	v_mul_f32_e32 v95, v95, v99
	v_mul_f32_e32 v88, v88, v96
	v_mul_f32_e32 v89, v89, v97
	v_mul_f32_e32 v84, v84, v96
	v_mul_f32_e32 v85, v85, v97
	v_mul_f32_e32 v86, v86, v98
	v_mul_f32_e32 v87, v87, v99
	v_mul_f32_e32 v96, v80, v96
	v_mul_f32_e32 v97, v81, v97
	v_cvt_pk_bf16_f32 v80, v92, v93
	v_cvt_pk_bf16_f32 v81, v94, v95
	v_mul_f32_e32 v90, v90, v98
	v_mul_f32_e32 v91, v91, v99
	v_mul_f32_e32 v98, v82, v98
	v_mul_f32_e32 v99, v83, v99
	v_cvt_pk_bf16_f32 v82, v88, v89
	v_cvt_pk_bf16_f32 v83, v90, v91
	v_cvt_pk_bf16_f32 v84, v84, v85
	v_cvt_pk_bf16_f32 v85, v86, v87
	v_cvt_pk_bf16_f32 v86, v96, v97
	v_cvt_pk_bf16_f32 v87, v98, v99
	global_store_dwordx2 v[124:125], v[80:81], off offset:64
	global_store_dwordx2 v[124:125], v[82:83], off offset:2112
	global_store_dwordx2 v[104:105], v[84:85], off
	global_store_dwordx2 v[102:103], v[86:87], off
	v_or_b32_e32 v84, 64, v120
	v_ashrrev_i32_e32 v85, 31, v84
	v_lshl_add_u64 v[86:87], v[84:85], 2, s[14:15]
	global_load_dwordx4 v[250:253], v[86:87], off
	v_lshl_add_u64 v[88:89], v[126:127], 0, s[36:37]
	v_lshl_add_u64 v[90:91], v[88:89], 0, v[116:117]
	v_lshl_add_u64 v[88:89], v[88:89], 0, v[118:119]
	s_waitcnt vmcnt(5)
	v_mov_b32_e32 v80, v246
	v_mov_b32_e32 v81, v247
	v_mov_b32_e32 v82, v248
	v_mov_b32_e32 v83, v249
	v_pk_fma_f32 v[80:81], v[80:81], s[30:31], v[112:113] op_sel_hi:[1,0,0]
	v_pk_fma_f32 v[82:83], v[82:83], s[30:31], v[112:113] op_sel_hi:[1,0,0]
	v_mul_f32_e32 v85, 0x4b800000, v80
	v_mul_f32_e32 v92, 0x4b800000, v81
	v_mul_f32_e32 v93, 0x4b800000, v82
	v_mul_f32_e32 v94, 0x4b800000, v83
	v_cmp_gt_f32_e32 vcc, s40, v80
	v_cmp_gt_f32_e64 s[0:1], s40, v81
	v_cmp_gt_f32_e64 s[10:11], s40, v82
	v_cmp_gt_f32_e64 s[12:13], s40, v83
	v_cndmask_b32_e32 v80, v80, v85, vcc
	v_cndmask_b32_e64 v81, v81, v92, s[0:1]
	v_cndmask_b32_e64 v82, v82, v93, s[10:11]
	v_cndmask_b32_e64 v83, v83, v94, s[12:13]
	v_rsq_f32_e32 v80, v80
	v_rsq_f32_e32 v81, v81
	v_rsq_f32_e32 v82, v82
	v_rsq_f32_e32 v83, v83
	v_mul_f32_e32 v85, 0x45800000, v80
	v_mul_f32_e32 v92, 0x45800000, v81
	v_mul_f32_e32 v93, 0x45800000, v82
	v_mul_f32_e32 v94, 0x45800000, v83
	v_cndmask_b32_e32 v80, v80, v85, vcc
	v_cndmask_b32_e64 v81, v81, v92, s[0:1]
	v_cndmask_b32_e64 v82, v82, v93, s[10:11]
	v_cndmask_b32_e64 v83, v83, v94, s[12:13]
	v_mul_f32_e32 v76, v76, v80
	v_mul_f32_e32 v77, v77, v81
	v_mul_f32_e32 v78, v78, v82
	v_mul_f32_e32 v79, v79, v83
	v_mul_f32_e32 v72, v72, v80
	v_mul_f32_e32 v73, v73, v81
	v_mul_f32_e32 v68, v68, v80
	v_mul_f32_e32 v69, v69, v81
	v_mul_f32_e32 v70, v70, v82
	v_mul_f32_e32 v71, v71, v83
	v_mul_f32_e32 v80, v64, v80
	v_mul_f32_e32 v81, v65, v81
	v_cvt_pk_bf16_f32 v64, v76, v77
	v_cvt_pk_bf16_f32 v65, v78, v79
	v_mul_f32_e32 v74, v74, v82
	v_mul_f32_e32 v75, v75, v83
	v_mul_f32_e32 v82, v66, v82
	v_mul_f32_e32 v83, v67, v83
	v_cvt_pk_bf16_f32 v66, v72, v73
	v_cvt_pk_bf16_f32 v67, v74, v75
	v_cvt_pk_bf16_f32 v68, v68, v69
	v_cvt_pk_bf16_f32 v69, v70, v71
	v_cvt_pk_bf16_f32 v70, v80, v81
	v_cvt_pk_bf16_f32 v71, v82, v83
	global_store_dwordx2 v[124:125], v[64:65], off offset:96
	global_store_dwordx2 v[124:125], v[66:67], off offset:2144
	global_store_dwordx2 v[90:91], v[68:69], off
	global_store_dwordx2 v[88:89], v[70:71], off
	v_or_b32_e32 v68, 0x50, v120
	v_ashrrev_i32_e32 v69, 31, v68
	v_lshl_add_u64 v[70:71], v[68:69], 2, s[14:15]
	global_load_dwordx4 v[246:249], v[70:71], off
	v_lshrrev_b32_e32 v72, 6, v84
	v_and_or_b32 v122, v72, s50, v121
	v_lshlrev_b64 v[72:73], 14, v[122:123]
	v_lshl_add_u64 v[72:73], s[38:39], 0, v[72:73]
	v_lshl_add_u64 v[72:73], v[72:73], 0, v[152:153]
	v_lshl_add_u64 v[74:75], v[72:73], 0, v[114:115]
	v_lshl_add_u64 v[76:77], v[72:73], 0, v[116:117]
	v_lshl_add_u64 v[72:73], v[72:73], 0, v[118:119]
	s_waitcnt vmcnt(5)
	v_mov_b32_e32 v64, v250
	v_mov_b32_e32 v65, v251
	v_mov_b32_e32 v66, v252
	v_mov_b32_e32 v67, v253
	v_pk_fma_f32 v[64:65], v[64:65], s[30:31], v[112:113] op_sel_hi:[1,0,0]
	v_pk_fma_f32 v[66:67], v[66:67], s[30:31], v[112:113] op_sel_hi:[1,0,0]
	v_mul_f32_e32 v69, 0x4b800000, v64
	v_mul_f32_e32 v78, 0x4b800000, v65
	v_mul_f32_e32 v79, 0x4b800000, v66
	v_mul_f32_e32 v80, 0x4b800000, v67
	v_cmp_gt_f32_e32 vcc, s40, v64
	v_cmp_gt_f32_e64 s[0:1], s40, v65
	v_cmp_gt_f32_e64 s[10:11], s40, v66
	v_cmp_gt_f32_e64 s[12:13], s40, v67
	v_cndmask_b32_e32 v64, v64, v69, vcc
	v_cndmask_b32_e64 v65, v65, v78, s[0:1]
	v_cndmask_b32_e64 v66, v66, v79, s[10:11]
	v_cndmask_b32_e64 v67, v67, v80, s[12:13]
	v_rsq_f32_e32 v64, v64
	v_rsq_f32_e32 v65, v65
	v_rsq_f32_e32 v66, v66
	v_rsq_f32_e32 v67, v67
	v_mul_f32_e32 v69, 0x45800000, v64
	v_mul_f32_e32 v78, 0x45800000, v65
	v_mul_f32_e32 v79, 0x45800000, v66
	v_mul_f32_e32 v80, 0x45800000, v67
	v_cndmask_b32_e32 v64, v64, v69, vcc
	v_cndmask_b32_e64 v65, v65, v78, s[0:1]
	v_cndmask_b32_e64 v66, v66, v79, s[10:11]
	v_cndmask_b32_e64 v67, v67, v80, s[12:13]
	v_mul_f32_e32 v60, v60, v64
	v_mul_f32_e32 v61, v61, v65
	v_mul_f32_e32 v62, v62, v66
	v_mul_f32_e32 v63, v63, v67
	v_mul_f32_e32 v56, v56, v64
	v_mul_f32_e32 v57, v57, v65
	v_mul_f32_e32 v52, v52, v64
	v_mul_f32_e32 v53, v53, v65
	v_mul_f32_e32 v54, v54, v66
	v_mul_f32_e32 v55, v55, v67
	v_mul_f32_e32 v64, v48, v64
	v_mul_f32_e32 v65, v49, v65
	v_cvt_pk_bf16_f32 v48, v60, v61
	v_cvt_pk_bf16_f32 v49, v62, v63
	v_mul_f32_e32 v58, v58, v66
	v_mul_f32_e32 v59, v59, v67
	v_mul_f32_e32 v66, v50, v66
	v_mul_f32_e32 v67, v51, v67
	v_cvt_pk_bf16_f32 v50, v56, v57
	v_cvt_pk_bf16_f32 v51, v58, v59
	v_cvt_pk_bf16_f32 v52, v52, v53
	v_cvt_pk_bf16_f32 v53, v54, v55
	v_cvt_pk_bf16_f32 v54, v64, v65
	v_cvt_pk_bf16_f32 v55, v66, v67
	global_store_dwordx2 v[74:75], v[48:49], off
	global_store_dwordx2 v[74:75], v[50:51], off offset:2048
	global_store_dwordx2 v[76:77], v[52:53], off
	global_store_dwordx2 v[72:73], v[54:55], off
	v_or_b32_e32 v52, 0x60, v120
	v_ashrrev_i32_e32 v53, 31, v52
	v_lshl_add_u64 v[54:55], v[52:53], 2, s[14:15]
	global_load_dwordx4 v[250:253], v[54:55], off
	v_lshrrev_b32_e32 v56, 6, v68
	v_and_or_b32 v122, v56, s50, v121
	v_lshlrev_b64 v[56:57], 14, v[122:123]
	v_lshl_add_u64 v[56:57], s[38:39], 0, v[56:57]
	v_lshl_add_u64 v[56:57], v[56:57], 0, v[152:153]
	v_lshl_add_u64 v[58:59], v[56:57], 0, 32
	v_lshl_add_u64 v[56:57], v[56:57], 0, v[114:115]
	v_lshl_add_u64 v[60:61], v[58:59], 0, v[116:117]
	v_lshl_add_u64 v[58:59], v[58:59], 0, v[118:119]
	s_waitcnt vmcnt(5)
	v_mov_b32_e32 v48, v246
	v_mov_b32_e32 v49, v247
	v_mov_b32_e32 v50, v248
	v_mov_b32_e32 v51, v249
	v_pk_fma_f32 v[48:49], v[48:49], s[30:31], v[112:113] op_sel_hi:[1,0,0]
	v_pk_fma_f32 v[50:51], v[50:51], s[30:31], v[112:113] op_sel_hi:[1,0,0]
	v_mul_f32_e32 v53, 0x4b800000, v48
	v_mul_f32_e32 v62, 0x4b800000, v49
	v_mul_f32_e32 v63, 0x4b800000, v50
	v_mul_f32_e32 v64, 0x4b800000, v51
	v_cmp_gt_f32_e32 vcc, s40, v48
	v_cmp_gt_f32_e64 s[0:1], s40, v49
	v_cmp_gt_f32_e64 s[10:11], s40, v50
	v_cmp_gt_f32_e64 s[12:13], s40, v51
	v_cndmask_b32_e32 v48, v48, v53, vcc
	v_cndmask_b32_e64 v49, v49, v62, s[0:1]
	v_cndmask_b32_e64 v50, v50, v63, s[10:11]
	v_cndmask_b32_e64 v51, v51, v64, s[12:13]
	v_rsq_f32_e32 v48, v48
	v_rsq_f32_e32 v49, v49
	v_rsq_f32_e32 v50, v50
	v_rsq_f32_e32 v51, v51
	v_mul_f32_e32 v53, 0x45800000, v48
	v_mul_f32_e32 v62, 0x45800000, v49
	v_mul_f32_e32 v63, 0x45800000, v50
	v_mul_f32_e32 v64, 0x45800000, v51
	v_cndmask_b32_e32 v48, v48, v53, vcc
	v_cndmask_b32_e64 v49, v49, v62, s[0:1]
	v_cndmask_b32_e64 v50, v50, v63, s[10:11]
	v_cndmask_b32_e64 v51, v51, v64, s[12:13]
	v_mul_f32_e32 v44, v44, v48
	v_mul_f32_e32 v45, v45, v49
	v_mul_f32_e32 v46, v46, v50
	v_mul_f32_e32 v47, v47, v51
	v_mul_f32_e32 v40, v40, v48
	v_mul_f32_e32 v41, v41, v49
	v_mul_f32_e32 v36, v36, v48
	v_mul_f32_e32 v37, v37, v49
	v_mul_f32_e32 v38, v38, v50
	v_mul_f32_e32 v39, v39, v51
	v_mul_f32_e32 v48, v32, v48
	v_mul_f32_e32 v49, v33, v49
	v_cvt_pk_bf16_f32 v32, v44, v45
	v_cvt_pk_bf16_f32 v33, v46, v47
	v_mul_f32_e32 v42, v42, v50
	v_mul_f32_e32 v43, v43, v51
	v_mul_f32_e32 v50, v34, v50
	v_mul_f32_e32 v51, v35, v51
	v_cvt_pk_bf16_f32 v34, v40, v41
	v_cvt_pk_bf16_f32 v35, v42, v43
	v_cvt_pk_bf16_f32 v36, v36, v37
	v_cvt_pk_bf16_f32 v37, v38, v39
	v_cvt_pk_bf16_f32 v38, v48, v49
	v_cvt_pk_bf16_f32 v39, v50, v51
	global_store_dwordx2 v[56:57], v[32:33], off offset:32
	global_store_dwordx2 v[56:57], v[34:35], off offset:2080
	global_store_dwordx2 v[60:61], v[36:37], off
	global_store_dwordx2 v[58:59], v[38:39], off
	v_or_b32_e32 v36, 0x70, v120
	v_ashrrev_i32_e32 v37, 31, v36
	v_lshl_add_u64 v[38:39], v[36:37], 2, s[14:15]
	global_load_dwordx4 v[246:249], v[38:39], off
	v_lshrrev_b32_e32 v40, 6, v52
	v_and_or_b32 v122, v40, s50, v121
	v_lshlrev_b64 v[40:41], 14, v[122:123]
	v_lshl_add_u64 v[40:41], s[38:39], 0, v[40:41]
	v_lshl_add_u64 v[40:41], v[40:41], 0, v[152:153]
	v_lshl_add_u64 v[42:43], v[40:41], 0, 64
	v_lshl_add_u64 v[40:41], v[40:41], 0, v[114:115]
	v_lshl_add_u64 v[44:45], v[42:43], 0, v[116:117]
	v_lshl_add_u64 v[42:43], v[42:43], 0, v[118:119]
	s_waitcnt vmcnt(5)
	v_mov_b32_e32 v32, v250
	v_mov_b32_e32 v33, v251
	v_mov_b32_e32 v34, v252
	v_mov_b32_e32 v35, v253
	v_pk_fma_f32 v[32:33], v[32:33], s[30:31], v[112:113] op_sel_hi:[1,0,0]
	v_pk_fma_f32 v[34:35], v[34:35], s[30:31], v[112:113] op_sel_hi:[1,0,0]
	v_mul_f32_e32 v37, 0x4b800000, v32
	v_mul_f32_e32 v46, 0x4b800000, v33
	v_mul_f32_e32 v47, 0x4b800000, v34
	v_mul_f32_e32 v48, 0x4b800000, v35
	v_cmp_gt_f32_e32 vcc, s40, v32
	v_cmp_gt_f32_e64 s[0:1], s40, v33
	v_cmp_gt_f32_e64 s[10:11], s40, v34
	v_cmp_gt_f32_e64 s[12:13], s40, v35
	v_cndmask_b32_e32 v32, v32, v37, vcc
	v_cndmask_b32_e64 v33, v33, v46, s[0:1]
	v_cndmask_b32_e64 v34, v34, v47, s[10:11]
	v_cndmask_b32_e64 v35, v35, v48, s[12:13]
	v_rsq_f32_e32 v32, v32
	v_rsq_f32_e32 v33, v33
	v_rsq_f32_e32 v34, v34
	v_rsq_f32_e32 v35, v35
	v_mul_f32_e32 v37, 0x45800000, v32
	v_mul_f32_e32 v46, 0x45800000, v33
	v_mul_f32_e32 v47, 0x45800000, v34
	v_mul_f32_e32 v48, 0x45800000, v35
	v_cndmask_b32_e32 v32, v32, v37, vcc
	v_cndmask_b32_e64 v33, v33, v46, s[0:1]
	v_cndmask_b32_e64 v34, v34, v47, s[10:11]
	v_cndmask_b32_e64 v35, v35, v48, s[12:13]
	v_mul_f32_e32 v28, v28, v32
	v_mul_f32_e32 v29, v29, v33
	v_mul_f32_e32 v30, v30, v34
	v_mul_f32_e32 v31, v31, v35
	v_mul_f32_e32 v24, v24, v32
	v_mul_f32_e32 v25, v25, v33
	v_mul_f32_e32 v20, v20, v32
	v_mul_f32_e32 v21, v21, v33
	v_mul_f32_e32 v22, v22, v34
	v_mul_f32_e32 v23, v23, v35
	v_mul_f32_e32 v32, v16, v32
	v_mul_f32_e32 v33, v17, v33
	v_cvt_pk_bf16_f32 v16, v28, v29
	v_cvt_pk_bf16_f32 v17, v30, v31
	v_mul_f32_e32 v26, v26, v34
	v_mul_f32_e32 v27, v27, v35
	v_mul_f32_e32 v34, v18, v34
	v_mul_f32_e32 v35, v19, v35
	v_cvt_pk_bf16_f32 v18, v24, v25
	v_cvt_pk_bf16_f32 v19, v26, v27
	v_cvt_pk_bf16_f32 v20, v20, v21
	v_cvt_pk_bf16_f32 v21, v22, v23
	v_cvt_pk_bf16_f32 v22, v32, v33
	v_cvt_pk_bf16_f32 v23, v34, v35
	global_store_dwordx2 v[40:41], v[16:17], off offset:64
	global_store_dwordx2 v[40:41], v[18:19], off offset:2112
	global_store_dwordx2 v[44:45], v[20:21], off
	global_store_dwordx2 v[42:43], v[22:23], off
	v_lshrrev_b32_e32 v20, 6, v36
	v_and_or_b32 v122, v20, s50, v121
	v_lshlrev_b64 v[20:21], 14, v[122:123]
	v_lshl_add_u64 v[20:21], s[38:39], 0, v[20:21]
	v_lshl_add_u64 v[20:21], v[20:21], 0, v[152:153]
	v_lshl_add_u64 v[22:23], v[20:21], 0, s[36:37]
	v_lshl_add_u64 v[20:21], v[20:21], 0, v[114:115]
	v_lshl_add_u64 v[24:25], v[22:23], 0, v[116:117]
	v_lshl_add_u64 v[22:23], v[22:23], 0, v[118:119]
	s_waitcnt vmcnt(4)
	v_mov_b32_e32 v16, v246
	v_mov_b32_e32 v17, v247
	v_mov_b32_e32 v18, v248
	v_mov_b32_e32 v19, v249
	v_pk_fma_f32 v[16:17], v[16:17], s[30:31], v[112:113] op_sel_hi:[1,0,0]
	v_pk_fma_f32 v[18:19], v[18:19], s[30:31], v[112:113] op_sel_hi:[1,0,0]
	v_mul_f32_e32 v26, 0x4b800000, v16
	v_mul_f32_e32 v27, 0x4b800000, v17
	v_mul_f32_e32 v28, 0x4b800000, v18
	v_mul_f32_e32 v29, 0x4b800000, v19
	v_cmp_gt_f32_e32 vcc, s40, v16
	v_cmp_gt_f32_e64 s[0:1], s40, v17
	v_cmp_gt_f32_e64 s[10:11], s40, v18
	v_cmp_gt_f32_e64 s[12:13], s40, v19
	v_cndmask_b32_e32 v16, v16, v26, vcc
	v_cndmask_b32_e64 v17, v17, v27, s[0:1]
	v_cndmask_b32_e64 v18, v18, v28, s[10:11]
	v_cndmask_b32_e64 v19, v19, v29, s[12:13]
	v_rsq_f32_e32 v16, v16
	v_rsq_f32_e32 v17, v17
	v_rsq_f32_e32 v18, v18
	v_rsq_f32_e32 v19, v19
	v_mul_f32_e32 v26, 0x45800000, v16
	v_mul_f32_e32 v27, 0x45800000, v17
	v_mul_f32_e32 v28, 0x45800000, v18
	v_mul_f32_e32 v29, 0x45800000, v19
	v_cndmask_b32_e32 v16, v16, v26, vcc
	v_cndmask_b32_e64 v17, v17, v27, s[0:1]
	v_cndmask_b32_e64 v18, v18, v28, s[10:11]
	v_cndmask_b32_e64 v19, v19, v29, s[12:13]
	v_mul_f32_e32 v12, v12, v16
	v_mul_f32_e32 v13, v13, v17
	v_mul_f32_e32 v14, v14, v18
	v_mul_f32_e32 v15, v15, v19
	v_mul_f32_e32 v8, v8, v16
	v_mul_f32_e32 v9, v9, v17
	v_mul_f32_e32 v4, v4, v16
	v_mul_f32_e32 v5, v5, v17
	v_mul_f32_e32 v6, v6, v18
	v_mul_f32_e32 v7, v7, v19
	v_mul_f32_e32 v16, v0, v16
	v_mul_f32_e32 v17, v1, v17
	v_cvt_pk_bf16_f32 v0, v12, v13
	v_cvt_pk_bf16_f32 v1, v14, v15
	v_mul_f32_e32 v10, v10, v18
	v_mul_f32_e32 v11, v11, v19
	v_mul_f32_e32 v18, v2, v18
	v_mul_f32_e32 v19, v3, v19
	v_cvt_pk_bf16_f32 v2, v8, v9
	v_cvt_pk_bf16_f32 v3, v10, v11
	v_cvt_pk_bf16_f32 v4, v4, v5
	v_cvt_pk_bf16_f32 v5, v6, v7
	v_cvt_pk_bf16_f32 v6, v16, v17
	v_cvt_pk_bf16_f32 v7, v18, v19
	global_store_dwordx2 v[20:21], v[0:1], off offset:96
	global_store_dwordx2 v[20:21], v[2:3], off offset:2144
	global_store_dwordx2 v[24:25], v[4:5], off
	global_store_dwordx2 v[22:23], v[6:7], off
	s_branch .LBB0_699
